# hg_b: V^T tiles of each 16-chunk group staged once per workgroup in LDS with coalesced loads, replacing 8x redundant per-wave global loads
# speedup vs baseline: 1.0198x; 1.0109x over previous
; #define LAS __attribute__((address_space(3)))
; __device__ __forceinline__ void hg_b_item(const Params& p, LAS unsigned char* lds, int item, bool dry = false) {
;     ...
;     LAS bf16_t* SB = (LAS bf16_t*)lds;
;     const int b = item >> 6, h = (item >> 3) & 7, es = item & 7;
;     const int fr = lane & 15, fq = lane >> 4;
;     const bf16_t* Z = (const bf16_t*)(WSP + WS_Z); bf16_t* OI = (bf16_t*)(WSP + WS_OI); const float* DEC = (const float*)(WSP + WS_DEC);
;     f32x4 S = (f32x4){0.f, 0.f, 0.f, 0.f};
;     const int eg = 16 * es + fr, dg = 16 * wave + fr;
;     const bf16_t* pV = Z + (size_t)(b * SEQ + (eg >> 1)) * ZW + 4096 + h * 128 + (eg & 1) * 64 + 8 * fq;
;     const bf16_t* pK = Z + (size_t)(b * SEQ + (dg >> 1)) * ZW + 3072 + h * 128 + (dg & 1) * 64 + 8 * fq;
;     const bf16_t* pQ = Z + (size_t)(b * SEQ + fr) * ZW + 2048 + h * 128 + 8 * fq;
;     bf16_t* pO = OI + (size_t)(b * SEQ + 4 * fq) * D + h * 128 + 16 * es + fr;
;     const float* pD = DEC + (size_t)((b * 8 + h) * 64) * 128 + dg;
;     __syncthreads();
.LBB0_202:
	s_lshl_b32 s4, s50, 3
	s_and_b32 s4, s4, 56
	s_and_b32 s5, s50, 0xffffffc0
	s_or_b32 s4, s4, s5
	s_bfe_u32 s5, s50, 0x30003
	s_or_b32 s8, s4, s5
	s_and_b64 s[4:5], s[6:7], exec
	v_readfirstlane_b32 s24, v34
	v_readfirstlane_b32 s25, v35
	v_mov_b32_e32 v3, v162
	s_cselect_b32 s4, s8, s50
	v_readfirstlane_b32 s5, v3
	s_ashr_i32 s51, s5, 6
	v_and_b32_e32 v8, 15, v3
	s_ashr_i32 s16, s4, 6
	v_lshl_or_b32 v2, s51, 4, v8
	s_lshl_b32 s55, s16, 12
	v_ashrrev_i32_e32 v0, 1, v2
	s_bfe_u32 s17, s4, 0x30003
	s_lshl_b32 s4, s4, 4
	v_add_u32_e32 v0, s55, v0
	s_and_b32 s54, s4, 0x70
	v_mad_i64_i32 v[22:23], s[4:5], v0, s3, 0
	v_or_b32_e32 v0, s55, v8
	v_mov_b64_e32 v[4:5], s[24:25]
	v_bfe_u32 v9, v3, 4, 2
	v_mad_i64_i32 v[4:5], s[4:5], v0, s3, v[4:5]
	s_lshl_b32 s8, s17, 8
	v_lshl_add_u64 v[4:5], v[4:5], 0, s[8:9]
	v_lshlrev_b32_e32 v0, 4, v9
	v_lshl_add_u64 v[4:5], v[4:5], 0, v[0:1]
	v_lshl_add_u64 v[24:25], v[4:5], 0, s[10:11]
	v_lshl_or_b32 v4, v9, 2, s55
	v_ashrrev_i32_e32 v5, 31, v4
	v_lshlrev_b64 v[4:5], 11, v[4:5]
	v_lshl_add_u64 v[4:5], s[24:25], 0, v[4:5]
	v_lshl_add_u64 v[4:5], v[4:5], 0, s[8:9]
	s_lshl_b32 s4, s54, 1
	s_mov_b32 s5, s9
	v_lshl_add_u64 v[4:5], v[4:5], 0, s[4:5]
	v_lshlrev_b32_e32 v6, 1, v8
	v_mov_b32_e32 v7, v1
	v_lshl_add_u64 v[4:5], v[4:5], 0, v[6:7]
	v_lshl_add_u64 v[26:27], v[4:5], 0, s[12:13]
	v_or_b32_e32 v5, s54, v8
	v_lshrrev_b16_e32 v5, 1, v5
	v_or_b32_e32 v5, s55, v5
	v_mad_i64_i32 v[28:29], s[4:5], v5, s3, 0
	v_lshlrev_b32_e32 v3, 7, v3
	v_or_b32_e32 v5, s8, v28
	v_and_b32_e32 v3, 0x80, v3
	s_lshl_b32 s16, s16, 9
	s_lshl_b32 s17, s17, 6
	v_mul_u32_u24_e32 v4, 0x110, v8
	v_or3_b32 v28, v5, v3, v0
	v_or_b32_e32 v5, s8, v22
	s_lshl_b32 s4, s51, 5
	v_add3_u32 v4, 0, v0, v4
	v_or3_b32 v22, v5, v3, v0
	v_mov_b32_e32 v0, s4
	s_or_b32 s4, s16, s17
	s_ashr_i32 s5, s4, 31
	v_mad_u32_u24 v0, v9, s26, v0
	s_lshl_b64 s[4:5], s[4:5], 9
	v_ashrrev_i32_e32 v3, 31, v2
	s_mul_i32 s56, s51, 0x1100
	v_or_b32_e32 v0, v0, v6
	v_lshl_add_u64 v[30:31], v[2:3], 2, s[4:5]
	v_mov_b32_e32 v2, v1
	v_mov_b32_e32 v3, v1
	v_add_u32_e32 v37, 0, v0
	v_mov_b32_e32 v0, v1
	v_add_u32_e32 v38, s56, v4
	v_mov_b64_e32 v[4:5], v[2:3]
	v_mov_b64_e32 v[2:3], v[0:1]
	v_lshrrev_b32_e32 v174, 4, v162
	v_and_b32_e32 v174, 7, v174
	v_and_b32_e32 v175, 15, v162
	s_lshr_b32 s98, s54, 1
	s_add_i32 s98, s98, s55
	v_add_u32_e32 v176, s98, v174
	v_mul_u32_u24_e32 v176, 0x3000, v176
	v_lshl_add_u32 v176, v175, 4, v176
	v_add_u32_e32 v176, s8, v176
	v_lshrrev_b32_e32 v177, 7, v162
	v_mul_u32_u24_e32 v170, 0xc0000, v177
	v_add_u32_e32 v170, v170, v176
	v_add_u32_e32 v170, 0x402000, v170
	global_load_dwordx4 v[80:83], v170, s[24:25]
	v_add_u32_e32 v96, 0x300000, v170
	global_load_dwordx4 v[84:87], v96, s[24:25]
	v_add_u32_e32 v97, 0x600000, v170
	global_load_dwordx4 v[88:91], v97, s[24:25]
	v_add_u32_e32 v98, 0x900000, v170
	global_load_dwordx4 v[92:95], v98, s[24:25]
	v_add_u32_e32 v170, 0xc00000, v170
	v_mul_u32_u24_e32 v171, 0x1100, v177
	v_lshrrev_b32_e32 v177, 3, v175
	v_lshl_add_u32 v177, v174, 1, v177
	v_mul_u32_u24_e32 v177, 0x90, v177
	v_and_b32_e32 v174, 7, v175
	v_lshl_add_u32 v177, v174, 4, v177
	v_add_u32_e32 v171, v171, v177
	v_add_u32_e32 v171, 0x12000, v171
	v_and_b32_e32 v174, 15, v162
	v_bfe_u32 v175, v162, 4, 2
	v_mul_u32_u24_e32 v172, 0x90, v174
	v_lshl_add_u32 v172, v175, 4, v172
	v_add_u32_e32 v172, 0x12000, v172
	s_waitcnt vmcnt(0)
	ds_write_b128 v171, v[80:83]
	ds_write_b128 v171, v[84:87] offset:17408
	ds_write_b128 v171, v[88:91] offset:34816
	ds_write_b128 v171, v[92:95] offset:52224
	s_waitcnt lgkmcnt(0)
	s_mov_b32 s8, 0
	s_barrier

; __device__ __forceinline__ unsigned f2bf(float f) { unsigned u = __float_as_uint(f); return (u + 0x7fffu + ((u >> 16) & 1u)) >> 16; }
; #define MFMA16(a, b, c) __builtin_amdgcn_mfma_f32_16x16x32_bf16((a), (b), (c), 0, 0, 0)
; __device__ __forceinline__ void hg_b_item(const Params& p, LAS unsigned char* lds, int item, bool dry = false) {
;     ...
;         for (int g = 0; g < 16; ++g) { const int n = 16 * G16 + g; const size_t ro = (size_t)n * 64 * ZW;
;             const float dec = pD[n * 128];
;             bf16x8 aV[2], bK[2];
; #pragma unroll
;             for (int k = 0; k < 2; ++k) { aV[k] = *(const bf16x8*)(pV + ro + 32 * k); bK[k] = *(const bf16x8*)(pK + ro + 32 * k); }
; #pragma unroll
;             for (int r = 0; r < 4; ++r) SB[g * 2176 + (4 * fq + r) * 136 + dg] = (bf16_t)f2bf(S[r]);
;             S = S * dec;
; #pragma unroll
;             for (int k = 0; k < 2; ++k) S = MFMA16(aV[k], bK[k], S); }
.LBB0_204:
	v_add_u32_e32 v173, s16, v172
	v_lshl_add_u64 v[14:15], s[24:25], 0, v[10:11]
	s_nop 1
	v_bfe_u32 v18, v3, 16, 1
	v_bfe_u32 v19, v4, 16, 1
	v_add3_u32 v40, v3, v18, s27
	v_add_co_u32_e64 v18, s[4:5], s28, v14
	v_lshl_add_u64 v[12:13], s[24:25], 0, v[8:9]
	v_add3_u32 v41, v4, v19, s27
	v_addc_co_u32_e64 v19, s[4:5], 0, v15, s[4:5]
	v_add_co_u32_e64 v44, s[4:5], s29, v12
	v_bfe_u32 v0, v2, 16, 1
	s_nop 0
	v_addc_co_u32_e64 v45, s[4:5], 0, v13, s[4:5]
	v_add_co_u32_e64 v52, s[4:5], s30, v14
	v_lshl_add_u64 v[16:17], s[24:25], 0, v[6:7]
	s_nop 0
	v_addc_co_u32_e64 v53, s[4:5], 0, v15, s[4:5]
	v_add_co_u32_e64 v60, s[4:5], s31, v12
	v_add_u32_e32 v39, s16, v37
	s_nop 0
	v_addc_co_u32_e64 v61, s[4:5], 0, v13, s[4:5]
	v_add_co_u32_e64 v68, s[4:5], s33, v14
	v_bfe_u32 v20, v5, 16, 1
	s_nop 0
	v_addc_co_u32_e64 v69, s[4:5], 0, v15, s[4:5]
	v_add_co_u32_e64 v76, s[4:5], s34, v12
	v_add3_u32 v21, v2, v0, s27
	s_nop 0
	v_addc_co_u32_e64 v77, s[4:5], 0, v13, s[4:5]
	v_add_co_u32_e64 v84, s[4:5], s35, v14
	v_add_co_u32_e32 v32, vcc, 0x402000, v14
	s_nop 0
	v_addc_co_u32_e64 v85, s[4:5], 0, v15, s[4:5]
	v_add_co_u32_e64 v92, s[4:5], s36, v12
	v_add3_u32 v20, v5, v20, s27
	s_nop 0
	v_addc_co_u32_e64 v93, s[4:5], 0, v13, s[4:5]
	v_add_co_u32_e64 v104, s[4:5], s37, v14
	global_load_dword v0, v[16:17], off
	global_load_dword v154, v[16:17], off offset:512
	global_load_dword v156, v[16:17], off offset:1024
	global_load_dword v158, v[16:17], off offset:1536
	global_load_dword v160, v[16:17], off offset:2048
	global_load_dword v164, v[16:17], off offset:2560
	global_load_dword v166, v[16:17], off offset:3072
	global_load_dword v168, v[16:17], off offset:3584
	v_addc_co_u32_e64 v105, s[4:5], 0, v15, s[4:5]
	v_add_co_u32_e64 v124, s[4:5], s40, v12
	ds_write_b16_d16_hi v39, v21
	ds_write_b16_d16_hi v39, v40 offset:272
	ds_write_b16_d16_hi v39, v41 offset:544
	ds_write_b16_d16_hi v39, v20 offset:816
	v_addc_co_u32_e64 v125, s[4:5], 0, v13, s[4:5]
	v_add_co_u32_e64 v132, s[4:5], s41, v14
	v_addc_co_u32_e32 v33, vcc, 0, v15, vcc
	s_nop 0
	v_addc_co_u32_e64 v133, s[4:5], 0, v15, s[4:5]
	v_add_co_u32_e64 v140, s[4:5], s43, v12
	s_add_i32 s16, s16, 0x8800
	s_nop 0
	v_addc_co_u32_e64 v141, s[4:5], 0, v13, s[4:5]
	v_add_co_u32_e64 v150, s[4:5], s45, v14
	v_lshl_add_u64 v[10:11], v[10:11], 0, s[14:15]
	s_nop 0
	v_addc_co_u32_e64 v151, s[4:5], 0, v15, s[4:5]
	ds_read_b128 v[14:17], v173 offset:4352
	s_nop 0
	ds_read_b128 v[18:21], v173 offset:4416
	s_nop 0
	global_load_dwordx4 v[40:43], v[44:45], off offset:2048
	s_nop 0
	global_load_dwordx4 v[44:47], v[44:45], off offset:2112
	s_nop 0
	ds_read_b128 v[48:51], v173 offset:8704
	s_nop 0
	ds_read_b128 v[52:55], v173 offset:8768
	s_nop 0
	global_load_dwordx4 v[56:59], v[60:61], off offset:2048
	s_nop 0
	global_load_dwordx4 v[60:63], v[60:61], off offset:2112
	s_nop 0
	ds_read_b128 v[64:67], v173 offset:13056
	s_nop 0
	ds_read_b128 v[68:71], v173 offset:13120
	s_nop 0
	global_load_dwordx4 v[72:75], v[76:77], off offset:2048
	s_nop 0
	global_load_dwordx4 v[76:79], v[76:77], off offset:2112
	s_nop 0
	ds_read_b128 v[80:83], v173 offset:17408
	s_nop 0
	ds_read_b128 v[84:87], v173 offset:17472
	s_nop 0
	global_load_dwordx4 v[88:91], v[92:93], off offset:2048
	s_nop 0
	global_load_dwordx4 v[92:95], v[92:93], off offset:2112
	s_nop 0
	global_load_dwordx4 v[96:99], v[124:125], off offset:2048
	ds_read_b128 v[100:103], v173 offset:21760
	s_nop 0
	ds_read_b128 v[104:107], v173 offset:21824
	s_nop 0
	ds_read_b128 v[108:111], v173 offset:0
	v_add_co_u32_e64 v152, s[4:5], s46, v12
	v_add_co_u32_e32 v12, vcc, 0x401000, v12
	s_nop 0
	v_addc_co_u32_e64 v153, s[4:5], 0, v13, s[4:5]
	v_addc_co_u32_e32 v13, vcc, 0, v13, vcc
	ds_read_b128 v[112:115], v173 offset:64
	global_load_dwordx4 v[116:119], v[12:13], off offset:2048
	global_load_dwordx4 v[120:123], v[12:13], off offset:2112
	s_nop 0
	global_load_dwordx4 v[124:127], v[124:125], off offset:2112
	s_nop 0
	ds_read_b128 v[128:131], v173 offset:26112
	s_nop 0
	ds_read_b128 v[132:135], v173 offset:26176
	s_nop 0
	global_load_dwordx4 v[136:139], v[140:141], off offset:2048
	s_nop 0
	global_load_dwordx4 v[140:143], v[140:141], off offset:2112
	s_nop 0
	ds_read_b128 v[144:147], v173 offset:30464
	v_lshl_add_u64 v[8:9], v[8:9], 0, s[14:15]
	v_lshl_add_u64 v[6:7], v[6:7], 0, s[18:19]
	s_cmp_eq_u32 s16, 0x11000
	s_waitcnt vmcnt(21)
	v_pk_mul_f32 v[4:5], v[4:5], v[0:1] op_sel_hi:[1,0]
	v_pk_mul_f32 v[2:3], v[2:3], v[0:1] op_sel_hi:[1,0]
	s_waitcnt vmcnt(4)
	s_nop 0
	s_waitcnt lgkmcnt(0)
	v_mfma_f32_16x16x32_bf16 v[2:5], v[108:111], v[116:119], v[2:5]
	ds_read_b128 v[108:111], v173 offset:30528
	global_load_dwordx4 v[116:119], v[152:153], off offset:2048
	s_nop 0
	global_load_dwordx4 v[150:153], v[152:153], off offset:2112
	s_waitcnt vmcnt(5)
; __device__ __forceinline__ unsigned f2bf(float f) { unsigned u = __float_as_uint(f); return (u + 0x7fffu + ((u >> 16) & 1u)) >> 16; }
; #define MFMA16(a, b, c) __builtin_amdgcn_mfma_f32_16x16x32_bf16((a), (b), (c), 0, 0, 0)
; __device__ __forceinline__ void hg_b_item(const Params& p, LAS unsigned char* lds, int item, bool dry = false) {
;     ...
;         for (int g = 0; g < 16; ++g) { const int n = 16 * G16 + g; const size_t ro = (size_t)n * 64 * ZW;
;             const float dec = pD[n * 128];
;             bf16x8 aV[2], bK[2];
; #pragma unroll
;             for (int k = 0; k < 2; ++k) { aV[k] = *(const bf16x8*)(pV + ro + 32 * k); bK[k] = *(const bf16x8*)(pK + ro + 32 * k); }
; #pragma unroll
;             for (int r = 0; r < 4; ++r) SB[g * 2176 + (4 * fq + r) * 136 + dg] = (bf16_t)f2bf(S[r]);
;             S = S * dec;
; #pragma unroll
;             for (int k = 0; k < 2; ++k) S = MFMA16(aV[k], bK[k], S); }
;         asm volatile("s_waitcnt lgkmcnt(0)" ::: "memory"); __builtin_amdgcn_s_barrier(); asm volatile("" ::: "memory");
	v_mfma_f32_16x16x32_bf16 v[2:5], v[112:115], v[120:123], v[2:5]
	s_nop 7
	v_bfe_u32 v0, v2, 16, 1
	v_bfe_u32 v12, v3, 16, 1
	v_bfe_u32 v13, v4, 16, 1
	v_bfe_u32 v32, v5, 16, 1
	v_pk_mul_f32 v[114:115], v[4:5], v[154:155] op_sel_hi:[1,0]
	v_pk_mul_f32 v[112:113], v[2:3], v[154:155] op_sel_hi:[1,0]
	v_add3_u32 v0, v2, v0, s27
	v_add3_u32 v12, v3, v12, s27
	v_add3_u32 v13, v4, v13, s27
	v_add3_u32 v32, v5, v32, s27
	v_mfma_f32_16x16x32_bf16 v[2:5], v[14:17], v[40:43], v[112:115]
	ds_write_b16_d16_hi v39, v0 offset:4352
	ds_write_b16_d16_hi v39, v12 offset:4624
	ds_write_b16_d16_hi v39, v13 offset:4896
	ds_write_b16_d16_hi v39, v32 offset:5168
	v_mfma_f32_16x16x32_bf16 v[2:5], v[18:21], v[44:47], v[2:5]
	s_nop 7
	v_bfe_u32 v0, v2, 16, 1
	v_bfe_u32 v16, v3, 16, 1
	v_bfe_u32 v17, v4, 16, 1
	v_bfe_u32 v18, v5, 16, 1
	v_pk_mul_f32 v[14:15], v[4:5], v[156:157] op_sel_hi:[1,0]
	v_pk_mul_f32 v[12:13], v[2:3], v[156:157] op_sel_hi:[1,0]
	v_add3_u32 v0, v2, v0, s27
	v_add3_u32 v16, v3, v16, s27
	v_add3_u32 v17, v4, v17, s27
	v_add3_u32 v18, v5, v18, s27
	v_mfma_f32_16x16x32_bf16 v[2:5], v[48:51], v[56:59], v[12:15]
	ds_write_b16_d16_hi v39, v0 offset:8704
	ds_write_b16_d16_hi v39, v16 offset:8976
	ds_write_b16_d16_hi v39, v17 offset:9248
	ds_write_b16_d16_hi v39, v18 offset:9520
	v_mfma_f32_16x16x32_bf16 v[2:5], v[52:55], v[60:63], v[2:5]
	s_nop 7
	v_bfe_u32 v0, v2, 16, 1
	v_bfe_u32 v16, v3, 16, 1
	v_bfe_u32 v17, v4, 16, 1
	v_bfe_u32 v18, v5, 16, 1
	v_pk_mul_f32 v[14:15], v[4:5], v[158:159] op_sel_hi:[1,0]
	v_pk_mul_f32 v[12:13], v[2:3], v[158:159] op_sel_hi:[1,0]
	v_add3_u32 v0, v2, v0, s27
	v_add3_u32 v16, v3, v16, s27
	v_add3_u32 v17, v4, v17, s27
	v_add3_u32 v18, v5, v18, s27
	v_mfma_f32_16x16x32_bf16 v[2:5], v[64:67], v[72:75], v[12:15]
	ds_write_b16_d16_hi v39, v0 offset:13056
	ds_write_b16_d16_hi v39, v16 offset:13328
	ds_write_b16_d16_hi v39, v17 offset:13600
	ds_write_b16_d16_hi v39, v18 offset:13872
	v_mfma_f32_16x16x32_bf16 v[2:5], v[68:71], v[76:79], v[2:5]
	s_nop 7
	v_bfe_u32 v0, v2, 16, 1
	v_bfe_u32 v16, v3, 16, 1
	v_bfe_u32 v17, v4, 16, 1
	v_bfe_u32 v18, v5, 16, 1
	v_pk_mul_f32 v[14:15], v[4:5], v[160:161] op_sel_hi:[1,0]
	v_pk_mul_f32 v[12:13], v[2:3], v[160:161] op_sel_hi:[1,0]
	v_add3_u32 v0, v2, v0, s27
	v_add3_u32 v16, v3, v16, s27
	v_add3_u32 v17, v4, v17, s27
	v_add3_u32 v18, v5, v18, s27
	v_mfma_f32_16x16x32_bf16 v[2:5], v[80:83], v[88:91], v[12:15]
	ds_write_b16_d16_hi v39, v0 offset:17408
	ds_write_b16_d16_hi v39, v16 offset:17680
	ds_write_b16_d16_hi v39, v17 offset:17952
	ds_write_b16_d16_hi v39, v18 offset:18224
	v_mfma_f32_16x16x32_bf16 v[2:5], v[84:87], v[92:95], v[2:5]
	s_nop 7
	v_bfe_u32 v0, v2, 16, 1
	v_bfe_u32 v16, v3, 16, 1
	v_bfe_u32 v17, v4, 16, 1
	v_bfe_u32 v18, v5, 16, 1
	v_pk_mul_f32 v[14:15], v[4:5], v[164:165] op_sel_hi:[1,0]
	v_pk_mul_f32 v[12:13], v[2:3], v[164:165] op_sel_hi:[1,0]
	v_add3_u32 v0, v2, v0, s27
	v_add3_u32 v16, v3, v16, s27
	v_add3_u32 v17, v4, v17, s27
	v_add3_u32 v18, v5, v18, s27
	v_mfma_f32_16x16x32_bf16 v[2:5], v[100:103], v[96:99], v[12:15]
	ds_write_b16_d16_hi v39, v0 offset:21760
	ds_write_b16_d16_hi v39, v16 offset:22032
	ds_write_b16_d16_hi v39, v17 offset:22304
	ds_write_b16_d16_hi v39, v18 offset:22576
	s_waitcnt vmcnt(4)
	v_mfma_f32_16x16x32_bf16 v[2:5], v[104:107], v[124:127], v[2:5]
	s_nop 7
	v_bfe_u32 v0, v2, 16, 1
	v_bfe_u32 v16, v3, 16, 1
	v_bfe_u32 v17, v4, 16, 1
	v_bfe_u32 v18, v5, 16, 1
	v_pk_mul_f32 v[14:15], v[4:5], v[166:167] op_sel_hi:[1,0]
	v_pk_mul_f32 v[12:13], v[2:3], v[166:167] op_sel_hi:[1,0]
	v_add3_u32 v0, v2, v0, s27
	v_add3_u32 v16, v3, v16, s27
	v_add3_u32 v17, v4, v17, s27
	v_add3_u32 v18, v5, v18, s27
	s_waitcnt vmcnt(3)
	v_mfma_f32_16x16x32_bf16 v[2:5], v[128:131], v[136:139], v[12:15]
	ds_write_b16_d16_hi v39, v0 offset:26112
	ds_write_b16_d16_hi v39, v16 offset:26384
	ds_write_b16_d16_hi v39, v17 offset:26656
	ds_write_b16_d16_hi v39, v18 offset:26928
	s_waitcnt vmcnt(2)
	v_mfma_f32_16x16x32_bf16 v[2:5], v[132:135], v[140:143], v[2:5]
	s_nop 7
	v_pk_mul_f32 v[14:15], v[4:5], v[168:169] op_sel_hi:[1,0]
	v_pk_mul_f32 v[12:13], v[2:3], v[168:169] op_sel_hi:[1,0]
	v_bfe_u32 v0, v2, 16, 1
	v_bfe_u32 v16, v3, 16, 1
	s_waitcnt vmcnt(1)
	v_mfma_f32_16x16x32_bf16 v[12:15], v[144:147], v[116:119], v[12:15]
	v_bfe_u32 v17, v4, 16, 1
	v_bfe_u32 v18, v5, 16, 1
	v_add3_u32 v0, v2, v0, s27
	v_add3_u32 v16, v3, v16, s27
	v_add3_u32 v17, v4, v17, s27
	v_add3_u32 v18, v5, v18, s27
	s_waitcnt vmcnt(0)
	s_waitcnt lgkmcnt(0)
	v_mfma_f32_16x16x32_bf16 v[2:5], v[108:111], v[150:153], v[12:15]
	ds_write_b16_d16_hi v39, v0 offset:30464
	ds_write_b16_d16_hi v39, v16 offset:30736
	ds_write_b16_d16_hi v39, v17 offset:31008
	ds_write_b16_d16_hi v39, v18 offset:31280
	s_cbranch_scc0 .LBB0_204
	s_lshl_b32 s16, s8, 4
	s_add_i32 s16, s16, s51
	s_waitcnt lgkmcnt(0)
	s_barrier
	s_cmp_eq_u32 s8, 3
	s_cbranch_scc1 .Lhgb_nostage
	global_load_dwordx4 v[80:83], v170, s[24:25]
	v_add_u32_e32 v96, 0x300000, v170
	global_load_dwordx4 v[84:87], v96, s[24:25]
	v_add_u32_e32 v97, 0x600000, v170
	global_load_dwordx4 v[88:91], v97, s[24:25]
	v_add_u32_e32 v98, 0x900000, v170
	global_load_dwordx4 v[92:95], v98, s[24:25]
	v_add_u32_e32 v170, 0xc00000, v170
; #define LAS __attribute__((address_space(3)))
; __device__ __forceinline__ unsigned f2bf(float f) { unsigned u = __float_as_uint(f); return (u + 0x7fffu + ((u >> 16) & 1u)) >> 16; }
; __device__ __forceinline__ float bf2f(unsigned h) { return __uint_as_float(h << 16); }
; #define MFMA16(a, b, c) __builtin_amdgcn_mfma_f32_16x16x32_bf16((a), (b), (c), 0, 0, 0)
; __device__ __forceinline__ void hg_b_item(const Params& p, LAS unsigned char* lds, int item, bool dry = false) {
;     ...
;         for (int c2 = 0; c2 < 2; ++c2) { const int g = wave + 8 * c2, nB = 16 * G16 + g; const size_t roB = (size_t)nB * 64 * ZW;
;             bf16x8 bS[4];
; #pragma unroll
;             for (int k = 0; k < 4; ++k) bS[k] = *(const LAS bf16x8*)(SB + g * 2176 + fr * 136 + 32 * k + 8 * fq);
; #pragma unroll
;             for (int lt = 0; lt < 4; ++lt) { f32x4 acc = (f32x4){0.f, 0.f, 0.f, 0.f}; unsigned short oO[4];
; #pragma unroll
;                 for (int r = 0; r < 4; ++r) oO[r] = pO[(size_t)(nB * 64 + 16 * lt + r) * D];
; #pragma unroll
;                 for (int k = 0; k < 4; ++k) { const bf16x8 a = *(const bf16x8*)(pQ + roB + (size_t)(16 * lt) * ZW + 32 * k); acc = MFMA16(a, bS[k], acc); }
; #pragma unroll
;                 for (int r = 0; r < 4; ++r) { const float nv = bf2f(oO[r]) + acc[r]; if (!dry) pO[(size_t)(nB * 64 + 16 * lt + r) * D] = (bf16_t)f2bf(nv); else if (nv == 123456.0f) pO[0] = 0; } } }
.Lhgb_nostage:
	v_mad_i64_i32 v[32:33], s[54:55], s16, v36, v[24:25]
	global_load_dwordx4 v[40:43], v[32:33], off
	global_load_dwordx4 v[44:47], v[32:33], off offset:64
	s_lshl_b32 s4, s16, 6
	s_ashr_i32 s5, s4, 31
	global_load_dwordx4 v[48:51], v[32:33], off offset:128
	s_lshl_b64 s[54:55], s[4:5], 11
	v_lshl_add_u64 v[56:57], v[26:27], 0, s[54:55]
	s_or_b32 s54, s4, 1
	s_ashr_i32 s55, s54, 31
	s_lshl_b64 s[54:55], s[54:55], 11
	v_lshl_add_u64 v[58:59], v[26:27], 0, s[54:55]
	s_or_b32 s54, s4, 2
	s_ashr_i32 s55, s54, 31
	s_lshl_b64 s[54:55], s[54:55], 11
	v_lshl_add_u64 v[60:61], v[26:27], 0, s[54:55]
	s_or_b32 s54, s4, 3
	s_ashr_i32 s55, s54, 31
	s_lshl_b64 s[54:55], s[54:55], 11
	v_lshl_add_u64 v[62:63], v[26:27], 0, s[54:55]
	global_load_ushort v0, v[56:57], off
	global_load_dwordx4 v[52:55], v[32:33], off offset:192
	global_load_ushort v39, v[58:59], off
	global_load_ushort v74, v[60:61], off
	global_load_ushort v75, v[62:63], off
	ds_read_b128 v[18:21], v38
	ds_read_b128 v[14:17], v38 offset:64
	ds_read_b128 v[10:13], v38 offset:128
	ds_read_b128 v[6:9], v38 offset:192
	s_or_b32 s54, s4, 16
	s_or_b32 s56, s4, 17
	s_or_b32 s58, s4, 18
	s_or_b32 s60, s4, 19
	s_ashr_i32 s55, s54, 31
	s_ashr_i32 s57, s56, 31
	s_ashr_i32 s59, s58, 31
	s_ashr_i32 s61, s60, 31
	s_lshl_b64 s[54:55], s[54:55], 11
	v_add_co_u32_e32 v64, vcc, s47, v32
	s_lshl_b64 s[56:57], s[56:57], 11
	s_lshl_b64 s[58:59], s[58:59], 11
	s_lshl_b64 s[60:61], s[60:61], 11
	v_lshl_add_u64 v[66:67], v[26:27], 0, s[54:55]
	v_addc_co_u32_e32 v65, vcc, 0, v33, vcc
	v_lshl_add_u64 v[68:69], v[26:27], 0, s[56:57]
	v_lshl_add_u64 v[70:71], v[26:27], 0, s[58:59]
	v_lshl_add_u64 v[72:73], v[26:27], 0, s[60:61]
	global_load_ushort v76, v[66:67], off
	global_load_ushort v77, v[68:69], off
	global_load_ushort v78, v[70:71], off
	global_load_ushort v79, v[72:73], off
	s_or_b32 s54, s4, 32
	s_or_b32 s56, s4, 33
	s_or_b32 s58, s4, 34
	s_or_b32 s60, s4, 35
	s_ashr_i32 s55, s54, 31
	s_ashr_i32 s57, s56, 31
	s_ashr_i32 s59, s58, 31
	s_ashr_i32 s61, s60, 31
	s_lshl_b64 s[54:55], s[54:55], 11
	s_lshl_b64 s[56:57], s[56:57], 11
	s_lshl_b64 s[58:59], s[58:59], 11
	s_lshl_b64 s[60:61], s[60:61], 11
	s_add_i32 s16, s16, 8
	s_add_i32 s8, s8, 1
	v_lshl_add_u64 v[28:29], v[28:29], 0, s[20:21]
	v_lshl_add_u64 v[22:23], v[22:23], 0, s[20:21]
	v_lshl_add_u64 v[30:31], v[30:31], 0, s[22:23]
	s_waitcnt vmcnt(11) lgkmcnt(3)
	v_mfma_f32_16x16x32_bf16 v[40:43], v[40:43], v[18:21], 0
	s_waitcnt vmcnt(8)
	v_lshlrev_b32_e32 v0, 16, v0
	s_waitcnt lgkmcnt(2)
	v_mfma_f32_16x16x32_bf16 v[40:43], v[44:47], v[14:17], v[40:43]
	s_waitcnt vmcnt(6)
	v_lshlrev_b32_e32 v39, 16, v39
	s_waitcnt vmcnt(5)
	v_lshlrev_b32_e32 v44, 16, v74
	s_waitcnt vmcnt(4)
	v_lshlrev_b32_e32 v45, 16, v75
	s_waitcnt lgkmcnt(1)
	v_mfma_f32_16x16x32_bf16 v[40:43], v[48:51], v[10:13], v[40:43]
	s_waitcnt lgkmcnt(0)
	v_mfma_f32_16x16x32_bf16 v[40:43], v[52:55], v[6:9], v[40:43]
	s_nop 7
	v_add_f32_e32 v0, v40, v0
	v_add_f32_e32 v39, v41, v39
	v_add_f32_e32 v40, v42, v44
	v_add_f32_e32 v41, v43, v45
	v_bfe_u32 v42, v0, 16, 1
	v_bfe_u32 v43, v39, 16, 1
	v_bfe_u32 v44, v40, 16, 1
	v_bfe_u32 v45, v41, 16, 1
	v_add3_u32 v0, v0, v42, s27
	v_add3_u32 v39, v39, v43, s27
	v_add3_u32 v40, v40, v44, s27
	v_add3_u32 v41, v41, v45, s27
	global_store_short_d16_hi v[56:57], v0, off
	global_store_short_d16_hi v[58:59], v39, off
	global_store_short_d16_hi v[60:61], v40, off
	global_store_short_d16_hi v[62:63], v41, off
	global_load_dwordx4 v[40:43], v[64:65], off
	s_nop 0
	global_load_dwordx4 v[44:47], v[64:65], off offset:64
	global_load_dwordx4 v[48:51], v[64:65], off offset:128
	global_load_dwordx4 v[52:55], v[64:65], off offset:192
	s_waitcnt vmcnt(11)
	v_lshlrev_b32_e32 v0, 16, v76
	s_waitcnt vmcnt(10)
	v_lshlrev_b32_e32 v39, 16, v77
	v_add_co_u32_e32 v56, vcc, s48, v32
	v_lshl_add_u64 v[58:59], v[26:27], 0, s[54:55]
	s_nop 0
	v_addc_co_u32_e32 v57, vcc, 0, v33, vcc
	v_lshl_add_u64 v[60:61], v[26:27], 0, s[56:57]
	v_lshl_add_u64 v[62:63], v[26:27], 0, s[58:59]
	v_lshl_add_u64 v[64:65], v[26:27], 0, s[60:61]
	v_add_co_u32_e32 v32, vcc, s49, v32
	s_or_b32 s54, s4, 48
	s_nop 0
	v_addc_co_u32_e32 v33, vcc, 0, v33, vcc
	s_or_b32 s56, s4, 49
	s_or_b32 s58, s4, 50
	s_or_b32 s4, s4, 51
	s_ashr_i32 s55, s54, 31
	s_ashr_i32 s57, s56, 31
	s_ashr_i32 s59, s58, 31
	s_ashr_i32 s5, s4, 31
	s_lshl_b64 s[54:55], s[54:55], 11
	s_lshl_b64 s[56:57], s[56:57], 11
	s_lshl_b64 s[58:59], s[58:59], 11
	s_lshl_b64 s[4:5], s[4:5], 11
	s_waitcnt vmcnt(3)
	v_mfma_f32_16x16x32_bf16 v[40:43], v[40:43], v[18:21], 0
	s_waitcnt vmcnt(2)
	v_mfma_f32_16x16x32_bf16 v[40:43], v[44:47], v[14:17], v[40:43]
	v_lshlrev_b32_e32 v44, 16, v78
	v_lshlrev_b32_e32 v45, 16, v79
	s_waitcnt vmcnt(1)
	v_mfma_f32_16x16x32_bf16 v[40:43], v[48:51], v[10:13], v[40:43]
	s_waitcnt vmcnt(0)
	v_mfma_f32_16x16x32_bf16 v[40:43], v[52:55], v[6:9], v[40:43]
	s_nop 7
	v_add_f32_e32 v0, v40, v0
	v_add_f32_e32 v39, v41, v39
	v_add_f32_e32 v40, v42, v44
	v_add_f32_e32 v41, v43, v45
	v_bfe_u32 v42, v0, 16, 1
	v_bfe_u32 v43, v39, 16, 1
	v_bfe_u32 v44, v40, 16, 1
	v_bfe_u32 v45, v41, 16, 1
	v_add3_u32 v0, v0, v42, s27
	v_add3_u32 v39, v39, v43, s27
	v_add3_u32 v40, v40, v44, s27
	v_add3_u32 v41, v41, v45, s27
	global_store_short_d16_hi v[66:67], v0, off
	global_store_short_d16_hi v[68:69], v39, off
	global_store_short_d16_hi v[70:71], v40, off
	global_store_short_d16_hi v[72:73], v41, off
	global_load_dwordx4 v[40:43], v[56:57], off
	s_nop 0
	global_load_dwordx4 v[44:47], v[56:57], off offset:64
	global_load_dwordx4 v[48:51], v[56:57], off offset:128
	global_load_ushort v0, v[58:59], off
	global_load_dwordx4 v[52:55], v[56:57], off offset:192
	global_load_ushort v39, v[60:61], off
	s_nop 0
	global_load_ushort v56, v[62:63], off
	global_load_ushort v57, v[64:65], off
	s_waitcnt vmcnt(7)
; #define LAS __attribute__((address_space(3)))
; __device__ __forceinline__ unsigned f2bf(float f) { unsigned u = __float_as_uint(f); return (u + 0x7fffu + ((u >> 16) & 1u)) >> 16; }
; __device__ __forceinline__ float bf2f(unsigned h) { return __uint_as_float(h << 16); }
; #define MFMA16(a, b, c) __builtin_amdgcn_mfma_f32_16x16x32_bf16((a), (b), (c), 0, 0, 0)
; __device__ __forceinline__ void hg_b_item(const Params& p, LAS unsigned char* lds, int item, bool dry = false) {
;     ...
;         for (int c2 = 0; c2 < 2; ++c2) { const int g = wave + 8 * c2, nB = 16 * G16 + g; const size_t roB = (size_t)nB * 64 * ZW;
;             bf16x8 bS[4];
; #pragma unroll
;             for (int k = 0; k < 4; ++k) bS[k] = *(const LAS bf16x8*)(SB + g * 2176 + fr * 136 + 32 * k + 8 * fq);
; #pragma unroll
;             for (int lt = 0; lt < 4; ++lt) { f32x4 acc = (f32x4){0.f, 0.f, 0.f, 0.f}; unsigned short oO[4];
; #pragma unroll
;                 for (int r = 0; r < 4; ++r) oO[r] = pO[(size_t)(nB * 64 + 16 * lt + r) * D];
; #pragma unroll
;                 for (int k = 0; k < 4; ++k) { const bf16x8 a = *(const bf16x8*)(pQ + roB + (size_t)(16 * lt) * ZW + 32 * k); acc = MFMA16(a, bS[k], acc); }
; #pragma unroll
;                 for (int r = 0; r < 4; ++r) { const float nv = bf2f(oO[r]) + acc[r]; if (!dry) pO[(size_t)(nB * 64 + 16 * lt + r) * D] = (bf16_t)f2bf(nv); else if (nv == 123456.0f) pO[0] = 0; } } }
	v_mfma_f32_16x16x32_bf16 v[40:43], v[40:43], v[18:21], 0
	s_waitcnt vmcnt(4)
	v_lshlrev_b32_e32 v0, 16, v0
	s_waitcnt vmcnt(2)
	v_lshlrev_b32_e32 v39, 16, v39
	v_mfma_f32_16x16x32_bf16 v[40:43], v[44:47], v[14:17], v[40:43]
	s_waitcnt vmcnt(1)
	v_lshlrev_b32_e32 v44, 16, v56
	s_waitcnt vmcnt(0)
	v_lshlrev_b32_e32 v45, 16, v57
	v_lshl_add_u64 v[56:57], v[26:27], 0, s[54:55]
	v_mfma_f32_16x16x32_bf16 v[40:43], v[48:51], v[10:13], v[40:43]
	v_mfma_f32_16x16x32_bf16 v[40:43], v[52:55], v[6:9], v[40:43]
	s_nop 7
	v_add_f32_e32 v0, v40, v0
	v_add_f32_e32 v39, v41, v39
	v_add_f32_e32 v40, v42, v44
	v_add_f32_e32 v41, v43, v45
	v_bfe_u32 v42, v0, 16, 1
	v_bfe_u32 v43, v39, 16, 1
	v_bfe_u32 v44, v40, 16, 1
	v_bfe_u32 v45, v41, 16, 1
	v_add3_u32 v0, v0, v42, s27
	v_add3_u32 v39, v39, v43, s27
	v_add3_u32 v40, v40, v44, s27
	v_add3_u32 v41, v41, v45, s27
	global_store_short_d16_hi v[58:59], v0, off
	global_store_short_d16_hi v[60:61], v39, off
	global_store_short_d16_hi v[62:63], v40, off
	global_store_short_d16_hi v[64:65], v41, off
	global_load_dwordx4 v[40:43], v[32:33], off
	v_lshl_add_u64 v[58:59], v[26:27], 0, s[56:57]
	global_load_dwordx4 v[44:47], v[32:33], off offset:64
	global_load_dwordx4 v[48:51], v[32:33], off offset:128
	v_lshl_add_u64 v[60:61], v[26:27], 0, s[58:59]
	v_lshl_add_u64 v[62:63], v[26:27], 0, s[4:5]
	global_load_ushort v0, v[56:57], off
	global_load_dwordx4 v[52:55], v[32:33], off offset:192
	global_load_ushort v39, v[58:59], off
	global_load_ushort v64, v[60:61], off
	global_load_ushort v65, v[62:63], off
	s_lshl_b32 s4, s16, 6
	v_mad_i64_i32 v[32:33], s[16:17], s16, v36, v[24:25]
	s_ashr_i32 s5, s4, 31
	s_or_b32 s16, s4, 1
	s_or_b32 s54, s4, 2
	s_or_b32 s56, s4, 3
	s_lshl_b64 s[58:59], s[4:5], 11
	s_ashr_i32 s17, s16, 31
	s_ashr_i32 s55, s54, 31
	s_ashr_i32 s57, s56, 31
	s_lshl_b64 s[16:17], s[16:17], 11
	s_lshl_b64 s[54:55], s[54:55], 11
	s_lshl_b64 s[56:57], s[56:57], 11
	s_waitcnt vmcnt(7)
	v_mfma_f32_16x16x32_bf16 v[18:21], v[40:43], v[18:21], 0
	s_waitcnt vmcnt(4)
	v_lshlrev_b32_e32 v0, 16, v0
	v_mfma_f32_16x16x32_bf16 v[14:17], v[44:47], v[14:17], v[18:21]
	v_mfma_f32_16x16x32_bf16 v[10:13], v[48:51], v[10:13], v[14:17]
	s_waitcnt vmcnt(3)
	v_mfma_f32_16x16x32_bf16 v[6:9], v[52:55], v[6:9], v[10:13]
	s_waitcnt vmcnt(2)
	s_nop 3
	v_lshlrev_b32_e32 v14, 16, v39
	s_waitcnt vmcnt(1)
	v_lshlrev_b32_e32 v15, 16, v64
	s_waitcnt vmcnt(0)
	v_lshlrev_b32_e32 v16, 16, v65
	v_add_co_u32_e32 v64, vcc, s47, v32
	s_nop 1
	v_addc_co_u32_e32 v65, vcc, 0, v33, vcc
	v_add_f32_e32 v0, v6, v0
	v_add_f32_e32 v6, v7, v14
	v_add_f32_e32 v7, v8, v15
	v_add_f32_e32 v8, v9, v16
	v_bfe_u32 v9, v0, 16, 1
	v_bfe_u32 v10, v6, 16, 1
	v_bfe_u32 v11, v7, 16, 1
	v_bfe_u32 v12, v8, 16, 1
	v_add3_u32 v0, v0, v9, s27
	v_add3_u32 v6, v6, v10, s27
	v_add3_u32 v7, v7, v11, s27
	v_add3_u32 v8, v8, v12, s27
	global_store_short_d16_hi v[56:57], v0, off
	global_store_short_d16_hi v[58:59], v6, off
	global_store_short_d16_hi v[60:61], v7, off
	global_store_short_d16_hi v[62:63], v8, off
	global_load_dwordx4 v[40:43], v[32:33], off
	global_load_dwordx4 v[44:47], v[32:33], off offset:64
	global_load_dwordx4 v[48:51], v[32:33], off offset:128
	v_lshl_add_u64 v[56:57], v[26:27], 0, s[58:59]
	v_lshl_add_u64 v[58:59], v[26:27], 0, s[16:17]
	v_lshl_add_u64 v[60:61], v[26:27], 0, s[54:55]
	v_lshl_add_u64 v[62:63], v[26:27], 0, s[56:57]
	global_load_ushort v0, v[56:57], off
	global_load_dwordx4 v[52:55], v[32:33], off offset:192
	global_load_ushort v39, v[58:59], off
	global_load_ushort v74, v[60:61], off
	global_load_ushort v75, v[62:63], off
	ds_read_b128 v[18:21], v38 offset:34816
	ds_read_b128 v[14:17], v38 offset:34880
	ds_read_b128 v[10:13], v38 offset:34944
	ds_read_b128 v[6:9], v38 offset:35008
	s_or_b32 s16, s4, 16
	s_or_b32 s54, s4, 17
	s_or_b32 s56, s4, 18
	s_or_b32 s58, s4, 19
	s_ashr_i32 s17, s16, 31
	s_ashr_i32 s55, s54, 31
	s_ashr_i32 s57, s56, 31
	s_waitcnt vmcnt(7) lgkmcnt(3)
	v_mfma_f32_16x16x32_bf16 v[40:43], v[40:43], v[18:21], 0
	s_waitcnt vmcnt(4)
	v_lshlrev_b32_e32 v0, 16, v0
	s_waitcnt vmcnt(2)
	v_lshlrev_b32_e32 v39, 16, v39
	s_ashr_i32 s59, s58, 31
	s_waitcnt lgkmcnt(2)
	v_mfma_f32_16x16x32_bf16 v[40:43], v[44:47], v[14:17], v[40:43]
	s_waitcnt vmcnt(1)
	v_lshlrev_b32_e32 v44, 16, v74
	s_waitcnt vmcnt(0)
	v_lshlrev_b32_e32 v45, 16, v75
	s_lshl_b64 s[16:17], s[16:17], 11
	s_waitcnt lgkmcnt(1)
	v_mfma_f32_16x16x32_bf16 v[40:43], v[48:51], v[10:13], v[40:43]
	s_lshl_b64 s[54:55], s[54:55], 11
	s_lshl_b64 s[56:57], s[56:57], 11
	s_lshl_b64 s[58:59], s[58:59], 11
	s_waitcnt lgkmcnt(0)
	v_mfma_f32_16x16x32_bf16 v[40:43], v[52:55], v[6:9], v[40:43]
	v_lshl_add_u64 v[66:67], v[26:27], 0, s[16:17]
	v_lshl_add_u64 v[68:69], v[26:27], 0, s[54:55]
	v_lshl_add_u64 v[70:71], v[26:27], 0, s[56:57]
	v_lshl_add_u64 v[72:73], v[26:27], 0, s[58:59]
	global_load_ushort v76, v[66:67], off
	global_load_ushort v77, v[68:69], off
	global_load_ushort v78, v[70:71], off
	global_load_ushort v79, v[72:73], off
	v_add_f32_e32 v0, v40, v0
	v_add_f32_e32 v39, v41, v39
	v_add_f32_e32 v40, v42, v44
	v_add_f32_e32 v41, v43, v45
	v_bfe_u32 v42, v0, 16, 1
	v_bfe_u32 v43, v39, 16, 1
	v_bfe_u32 v44, v40, 16, 1
	v_bfe_u32 v45, v41, 16, 1
	v_add3_u32 v0, v0, v42, s27
	v_add3_u32 v39, v39, v43, s27
	v_add3_u32 v40, v40, v44, s27
	v_add3_u32 v41, v41, v45, s27
	global_store_short_d16_hi v[56:57], v0, off
	global_store_short_d16_hi v[58:59], v39, off
	global_store_short_d16_hi v[60:61], v40, off
	global_store_short_d16_hi v[62:63], v41, off
	global_load_dwordx4 v[40:43], v[64:65], off
	s_nop 0
	global_load_dwordx4 v[44:47], v[64:65], off offset:64
	global_load_dwordx4 v[48:51], v[64:65], off offset:128
	global_load_dwordx4 v[52:55], v[64:65], off offset:192
	s_waitcnt vmcnt(3)
; #define LAS __attribute__((address_space(3)))
; __device__ __forceinline__ unsigned f2bf(float f) { unsigned u = __float_as_uint(f); return (u + 0x7fffu + ((u >> 16) & 1u)) >> 16; }
; __device__ __forceinline__ float bf2f(unsigned h) { return __uint_as_float(h << 16); }
; #define MFMA16(a, b, c) __builtin_amdgcn_mfma_f32_16x16x32_bf16((a), (b), (c), 0, 0, 0)
; __device__ __forceinline__ void hg_b_item(const Params& p, LAS unsigned char* lds, int item, bool dry = false) {
;     ...
;         for (int c2 = 0; c2 < 2; ++c2) { const int g = wave + 8 * c2, nB = 16 * G16 + g; const size_t roB = (size_t)nB * 64 * ZW;
;             bf16x8 bS[4];
; #pragma unroll
;             for (int k = 0; k < 4; ++k) bS[k] = *(const LAS bf16x8*)(SB + g * 2176 + fr * 136 + 32 * k + 8 * fq);
; #pragma unroll
;             for (int lt = 0; lt < 4; ++lt) { f32x4 acc = (f32x4){0.f, 0.f, 0.f, 0.f}; unsigned short oO[4];
; #pragma unroll
;                 for (int r = 0; r < 4; ++r) oO[r] = pO[(size_t)(nB * 64 + 16 * lt + r) * D];
; #pragma unroll
;                 for (int k = 0; k < 4; ++k) { const bf16x8 a = *(const bf16x8*)(pQ + roB + (size_t)(16 * lt) * ZW + 32 * k); acc = MFMA16(a, bS[k], acc); }
; #pragma unroll
;                 for (int r = 0; r < 4; ++r) { const float nv = bf2f(oO[r]) + acc[r]; if (!dry) pO[(size_t)(nB * 64 + 16 * lt + r) * D] = (bf16_t)f2bf(nv); else if (nv == 123456.0f) pO[0] = 0; } } }
;         asm volatile("s_waitcnt lgkmcnt(0)" ::: "memory"); __builtin_amdgcn_s_barrier(); asm volatile("" ::: "memory");
	v_mfma_f32_16x16x32_bf16 v[40:43], v[40:43], v[18:21], 0
	v_lshlrev_b32_e32 v0, 16, v76
	v_lshlrev_b32_e32 v39, 16, v77
	v_add_co_u32_e32 v56, vcc, s48, v32
	s_waitcnt vmcnt(2)
	v_mfma_f32_16x16x32_bf16 v[40:43], v[44:47], v[14:17], v[40:43]
	v_lshlrev_b32_e32 v44, 16, v78
	v_lshlrev_b32_e32 v45, 16, v79
	v_addc_co_u32_e32 v57, vcc, 0, v33, vcc
	s_waitcnt vmcnt(1)
	v_mfma_f32_16x16x32_bf16 v[40:43], v[48:51], v[10:13], v[40:43]
	s_or_b32 s16, s4, 32
	s_ashr_i32 s17, s16, 31
	s_lshl_b64 s[16:17], s[16:17], 11
	s_waitcnt vmcnt(0)
	v_mfma_f32_16x16x32_bf16 v[40:43], v[52:55], v[6:9], v[40:43]
	v_lshl_add_u64 v[58:59], v[26:27], 0, s[16:17]
	s_or_b32 s54, s4, 33
	s_or_b32 s56, s4, 34
	s_or_b32 s58, s4, 35
	s_ashr_i32 s55, s54, 31
	s_nop 2
	v_add_f32_e32 v0, v40, v0
	v_add_f32_e32 v39, v41, v39
	v_add_f32_e32 v40, v42, v44
	v_add_f32_e32 v41, v43, v45
	v_bfe_u32 v42, v0, 16, 1
	v_bfe_u32 v43, v39, 16, 1
	v_bfe_u32 v44, v40, 16, 1
	v_bfe_u32 v45, v41, 16, 1
	v_add3_u32 v0, v0, v42, s27
	v_add3_u32 v39, v39, v43, s27
	v_add3_u32 v40, v40, v44, s27
	v_add3_u32 v41, v41, v45, s27
	global_store_short_d16_hi v[66:67], v0, off
	global_store_short_d16_hi v[68:69], v39, off
	global_store_short_d16_hi v[70:71], v40, off
	global_store_short_d16_hi v[72:73], v41, off
	global_load_dwordx4 v[40:43], v[56:57], off
	s_ashr_i32 s57, s56, 31
	global_load_dwordx4 v[44:47], v[56:57], off offset:64
	global_load_dwordx4 v[48:51], v[56:57], off offset:128
	global_load_ushort v0, v[58:59], off
	global_load_dwordx4 v[52:55], v[56:57], off offset:192
	s_ashr_i32 s59, s58, 31
	s_lshl_b64 s[54:55], s[54:55], 11
	s_lshl_b64 s[56:57], s[56:57], 11
	s_lshl_b64 s[58:59], s[58:59], 11
	v_lshl_add_u64 v[60:61], v[26:27], 0, s[54:55]
	v_lshl_add_u64 v[62:63], v[26:27], 0, s[56:57]
	v_lshl_add_u64 v[64:65], v[26:27], 0, s[58:59]
	global_load_ushort v39, v[60:61], off
	global_load_ushort v56, v[62:63], off
	global_load_ushort v57, v[64:65], off
	s_waitcnt vmcnt(7)
	v_mfma_f32_16x16x32_bf16 v[40:43], v[40:43], v[18:21], 0
	s_waitcnt vmcnt(4)
	v_lshlrev_b32_e32 v0, 16, v0
	v_add_co_u32_e32 v32, vcc, s49, v32
	v_mfma_f32_16x16x32_bf16 v[40:43], v[44:47], v[14:17], v[40:43]
	s_nop 0
	v_addc_co_u32_e32 v33, vcc, 0, v33, vcc
	s_waitcnt vmcnt(2)
	v_lshlrev_b32_e32 v39, 16, v39
	v_mfma_f32_16x16x32_bf16 v[40:43], v[48:51], v[10:13], v[40:43]
	s_waitcnt vmcnt(1)
	v_lshlrev_b32_e32 v44, 16, v56
	s_waitcnt vmcnt(0)
	v_lshlrev_b32_e32 v45, 16, v57
	s_or_b32 s16, s4, 48
	v_mfma_f32_16x16x32_bf16 v[40:43], v[52:55], v[6:9], v[40:43]
	s_ashr_i32 s17, s16, 31
	s_lshl_b64 s[16:17], s[16:17], 11
	v_lshl_add_u64 v[52:53], v[26:27], 0, s[16:17]
	s_or_b32 s54, s4, 49
	s_or_b32 s56, s4, 50
	s_nop 2
	v_add_f32_e32 v0, v40, v0
	v_add_f32_e32 v39, v41, v39
	v_add_f32_e32 v40, v42, v44
	v_add_f32_e32 v41, v43, v45
	v_bfe_u32 v42, v0, 16, 1
	v_bfe_u32 v43, v39, 16, 1
	v_bfe_u32 v44, v40, 16, 1
	v_bfe_u32 v45, v41, 16, 1
	v_add3_u32 v0, v0, v42, s27
	v_add3_u32 v39, v39, v43, s27
	v_add3_u32 v40, v40, v44, s27
	v_add3_u32 v41, v41, v45, s27
	global_store_short_d16_hi v[58:59], v0, off
	global_store_short_d16_hi v[60:61], v39, off
	global_store_short_d16_hi v[62:63], v40, off
	global_store_short_d16_hi v[64:65], v41, off
	global_load_dwordx4 v[40:43], v[32:33], off
	s_nop 0
	global_load_dwordx4 v[44:47], v[32:33], off offset:64
	global_load_dwordx4 v[48:51], v[32:33], off offset:128
	s_waitcnt vmcnt(2)
	v_mfma_f32_16x16x32_bf16 v[18:21], v[40:43], v[18:21], 0
	global_load_ushort v0, v[52:53], off
	global_load_dwordx4 v[40:43], v[32:33], off offset:192
	s_or_b32 s4, s4, 51
	s_ashr_i32 s55, s54, 31
	s_ashr_i32 s57, s56, 31
	s_ashr_i32 s5, s4, 31
	s_lshl_b64 s[54:55], s[54:55], 11
	s_lshl_b64 s[56:57], s[56:57], 11
	s_lshl_b64 s[4:5], s[4:5], 11
	v_lshl_add_u64 v[54:55], v[26:27], 0, s[54:55]
	v_lshl_add_u64 v[56:57], v[26:27], 0, s[56:57]
	v_lshl_add_u64 v[58:59], v[26:27], 0, s[4:5]
	s_waitcnt vmcnt(3)
	v_mfma_f32_16x16x32_bf16 v[14:17], v[44:47], v[14:17], v[18:21]
	s_nop 2
	global_load_ushort v18, v[54:55], off
	global_load_ushort v19, v[56:57], off
	global_load_ushort v20, v[58:59], off
	s_cmp_eq_u32 s8, 4
	s_waitcnt vmcnt(4)
	v_lshlrev_b32_e32 v0, 16, v0
	v_mfma_f32_16x16x32_bf16 v[10:13], v[48:51], v[10:13], v[14:17]
	s_waitcnt vmcnt(3)
	v_mfma_f32_16x16x32_bf16 v[6:9], v[40:43], v[6:9], v[10:13]
	s_waitcnt vmcnt(2)
	v_lshlrev_b32_e32 v14, 16, v18
	s_waitcnt vmcnt(1)
	v_lshlrev_b32_e32 v15, 16, v19
	s_waitcnt vmcnt(0)
	v_lshlrev_b32_e32 v16, 16, v20
	s_nop 1
	v_add_f32_e32 v0, v6, v0
	v_add_f32_e32 v6, v7, v14
	v_add_f32_e32 v7, v8, v15
	v_add_f32_e32 v8, v9, v16
	v_bfe_u32 v9, v0, 16, 1
	v_bfe_u32 v10, v6, 16, 1
	v_bfe_u32 v11, v7, 16, 1
	v_bfe_u32 v12, v8, 16, 1
	v_add3_u32 v0, v0, v9, s27
	v_add3_u32 v6, v6, v10, s27
	v_add3_u32 v7, v7, v11, s27
	v_add3_u32 v8, v8, v12, s27
	global_store_short_d16_hi v[52:53], v0, off
	global_store_short_d16_hi v[54:55], v6, off
	global_store_short_d16_hi v[56:57], v7, off
	global_store_short_d16_hi v[58:59], v8, off
	ds_write_b128 v171, v[80:83]
	ds_write_b128 v171, v[84:87] offset:17408
	ds_write_b128 v171, v[88:91] offset:34816
	ds_write_b128 v171, v[92:95] offset:52224
	s_waitcnt lgkmcnt(0)
	s_barrier
	s_cbranch_scc0 .LBB0_203
	s_add_i32 s50, s50, s52
	s_cmpk_gt_i32 s50, 0xff
	s_cbranch_scc0 .LBB0_202

; __global__ void __launch_bounds__(NT, 2) mk_fwd(Params p) {
.Lfunc_end0:
	.size	_Z6mk_fwd6Params, .Lfunc_end0-_Z6mk_fwd6Params
	.set _Z6mk_fwd6Params.num_vgpr, 237
	.set _Z6mk_fwd6Params.num_agpr, 0
	.set _Z6mk_fwd6Params.numbered_sgpr, 102
	.set _Z6mk_fwd6Params.num_named_barrier, 0
	.set _Z6mk_fwd6Params.private_seg_size, 0
	.set _Z6mk_fwd6Params.uses_vcc, 1
	.set _Z6mk_fwd6Params.uses_flat_scratch, 0
	.set _Z6mk_fwd6Params.has_dyn_sized_stack, 0
	.set _Z6mk_fwd6Params.has_recursion, 0
	.set _Z6mk_fwd6Params.has_indirect_call, 0
